# v26 plus rescheduled hand-written half-unit epilogue: gate loads first, four rows interleaved, LDS transpose, 16-byte stores
# speedup vs baseline: 1.0021x; 1.0021x over previous
.LBB0_388:
	s_barrier
	s_waitcnt vmcnt(3)
	ds_write_b128 v82, v[50:53]
	s_waitcnt vmcnt(2)
	ds_write_b128 v82, v[54:57] offset:17408
	s_waitcnt vmcnt(1)
	ds_write_b128 v80, v[58:61]
	s_waitcnt vmcnt(0)
	ds_write_b128 v80, v[62:65] offset:17408
	s_waitcnt lgkmcnt(0)
	s_barrier
	ds_read_b128 v[116:119], v83
	ds_read_b128 v[74:77], v83 offset:64
	ds_read_b128 v[70:73], v83 offset:128
	ds_read_b128 v[66:69], v83 offset:192
	s_waitcnt lgkmcnt(3)
	v_mfma_f32_16x16x32_bf16 v[116:119], v[116:119], v[30:33], 0
	v_add_u32_e32 v56, s63, v103
	v_add_u32_e32 v120, s62, v101
	v_cvt_f32_i32_e32 v122, v56
	s_waitcnt lgkmcnt(2)
	v_mfma_f32_16x16x32_bf16 v[74:77], v[74:77], v[22:25], v[116:119]
	v_cvt_f32_i32_e32 v121, v120
	v_lshl_add_u64 v[50:51], v[88:89], 0, v[84:85]
	v_mul_f32_e32 v122, v99, v122
	s_waitcnt lgkmcnt(1)
	v_mfma_f32_16x16x32_bf16 v[70:73], v[70:73], v[14:17], v[74:77]
	v_add_co_u32_e32 v54, vcc, s5, v50
	v_mul_f32_e32 v121, v90, v121
	v_exp_f32_e32 v122, v122
	v_lshl_add_u64 v[52:53], v[86:87], 0, v[84:85]
	v_addc_co_u32_e32 v55, vcc, 0, v51, vcc
	v_exp_f32_e32 v121, v121
	v_add_co_u32_e32 v62, vcc, s5, v52
	s_waitcnt lgkmcnt(0)
	v_mfma_f32_16x16x32_bf16 v[66:69], v[66:69], v[10:13], v[70:73]
	v_addc_co_u32_e32 v63, vcc, 0, v53, vcc
	v_mul_f32_e32 v133, v98, v122
	v_mul_f32_e32 v135, v96, v122
	v_cmp_ne_u32_e32 vcc, s62, v115
	v_cmp_gt_i32_e64 s[10:11], 0, v120
	v_mul_f32_e32 v132, v97, v121
	v_mul_f32_e32 v134, v95, v121
	v_mul_f32_e32 v137, v94, v122
	v_cmp_ne_u32_e64 s[6:7], s62, v114
	v_mul_f32_e32 v122, v92, v122
	v_cmp_ne_u32_e64 s[8:9], s62, v113
	v_cndmask_b32_e64 v133, 2.0, v133, s[10:11]
	v_cndmask_b32_e32 v135, 2.0, v135, vcc
	v_cmp_lt_i32_e32 vcc, 1, v120
	v_cmp_lt_i32_e64 s[36:37], 0, v120
	v_add_u32_e32 v123, -16, v120
	v_subrev_u32_e32 v125, 32, v120
	v_subrev_u32_e32 v127, 48, v120
	v_mul_f32_e32 v136, v93, v121
	v_mul_f32_e32 v121, v91, v121
	v_cndmask_b32_e64 v137, 2.0, v137, s[6:7]
	v_cmp_lt_i32_e64 s[6:7], 2, v120
	v_cndmask_b32_e64 v122, 2.0, v122, s[8:9]
	v_cmp_lt_i32_e64 s[8:9], 3, v120
	v_cndmask_b32_e64 v120, v133, v132, s[36:37]
	v_cndmask_b32_e32 v132, v135, v134, vcc
	v_cndmask_b32_e64 v133, v137, v136, s[6:7]
	v_cndmask_b32_e64 v121, v122, v121, s[8:9]
	v_mul_f32_e32 v66, v120, v66
	v_mul_f32_e32 v67, v132, v67
	v_add_u32_e32 v124, 16, v56
	v_add_u32_e32 v126, 32, v56
	v_add_u32_e32 v128, 48, v56
	global_load_dwordx4 v[50:53], v[54:55], off offset:1024
	s_nop 0
	global_load_dwordx4 v[54:57], v[54:55], off offset:2048
	s_nop 0
	global_load_dwordx4 v[58:61], v[62:63], off offset:1024
	s_nop 0
	global_load_dwordx4 v[62:65], v[62:63], off offset:2048
	v_mul_f32_e32 v68, v133, v68
	v_mul_f32_e32 v69, v121, v69
	v_cvt_pk_bf16_f32 v66, v66, v67
	v_cvt_pk_bf16_f32 v67, v68, v69
	ds_write_b64 v100, v[66:67] offset:53248
	ds_read_b128 v[66:69], v83 offset:4352
	ds_read_b128 v[70:73], v83 offset:4416
	s_waitcnt lgkmcnt(1)
	v_mfma_f32_16x16x32_bf16 v[66:69], v[66:69], v[30:33], 0
	ds_read_b128 v[74:77], v83 offset:4480
	v_cvt_f32_i32_e32 v124, v124
	v_cvt_f32_i32_e32 v129, v123
	s_waitcnt lgkmcnt(1)
	v_mfma_f32_16x16x32_bf16 v[66:69], v[70:73], v[22:25], v[66:69]
	ds_read_b128 v[70:73], v83 offset:4544
	v_mul_f32_e32 v124, v99, v124
	v_mul_f32_e32 v129, v90, v129
	s_waitcnt lgkmcnt(1)
	v_mfma_f32_16x16x32_bf16 v[66:69], v[74:77], v[14:17], v[66:69]
	v_exp_f32_e32 v124, v124
	v_exp_f32_e32 v129, v129
	v_cmp_gt_i32_e64 s[10:11], 0, v123
	s_waitcnt lgkmcnt(0)
	v_mfma_f32_16x16x32_bf16 v[66:69], v[70:73], v[10:13], v[66:69]
	v_mul_f32_e32 v139, v98, v124
	v_mul_f32_e32 v141, v96, v124
	v_cmp_ne_u32_e64 s[12:13], s62, v110
	v_mul_f32_e32 v138, v97, v129
	v_mul_f32_e32 v140, v95, v129
	v_mul_f32_e32 v143, v94, v124
	v_cmp_ne_u32_e64 s[14:15], s62, v111
	v_mul_f32_e32 v124, v92, v124
	v_cmp_ne_u32_e64 s[16:17], s62, v112
	v_cndmask_b32_e64 v122, 2.0, v139, s[10:11]
	v_cmp_lt_i32_e32 vcc, 0, v123
	v_cndmask_b32_e64 v134, 2.0, v141, s[12:13]
	v_cmp_lt_i32_e64 s[6:7], 1, v123
	v_mul_f32_e32 v142, v93, v129
	v_mul_f32_e32 v129, v91, v129
	v_cndmask_b32_e64 v135, 2.0, v143, s[14:15]
	v_cmp_lt_i32_e64 s[8:9], 2, v123
	v_cndmask_b32_e64 v124, 2.0, v124, s[16:17]
	v_cmp_lt_i32_e64 s[10:11], 3, v123
	v_cndmask_b32_e32 v117, v122, v138, vcc
	v_cndmask_b32_e64 v118, v134, v140, s[6:7]
	v_cndmask_b32_e64 v119, v135, v142, s[8:9]
	v_cndmask_b32_e64 v74, v124, v129, s[10:11]
	v_mul_f32_e32 v66, v117, v66
	v_mul_f32_e32 v67, v118, v67
	v_mul_f32_e32 v68, v119, v68
	v_mul_f32_e32 v69, v74, v69
	v_cvt_pk_bf16_f32 v66, v66, v67
	v_cvt_pk_bf16_f32 v67, v68, v69
	ds_write_b64 v100, v[66:67] offset:53280
	ds_read_b128 v[66:69], v83 offset:8704
	ds_read_b128 v[70:73], v83 offset:8768
	s_waitcnt lgkmcnt(1)
	v_mfma_f32_16x16x32_bf16 v[66:69], v[66:69], v[30:33], 0
	ds_read_b128 v[74:77], v83 offset:8832
	v_cvt_f32_i32_e32 v126, v126
	v_cvt_f32_i32_e32 v130, v125
	s_waitcnt lgkmcnt(1)
	v_mfma_f32_16x16x32_bf16 v[66:69], v[70:73], v[22:25], v[66:69]
	ds_read_b128 v[70:73], v83 offset:8896
	v_mul_f32_e32 v126, v99, v126
	v_mul_f32_e32 v130, v90, v130
	s_waitcnt lgkmcnt(1)
	v_mfma_f32_16x16x32_bf16 v[66:69], v[74:77], v[14:17], v[66:69]
	v_exp_f32_e32 v126, v126
	v_exp_f32_e32 v130, v130
	v_cmp_gt_i32_e64 s[18:19], 0, v125
	s_waitcnt lgkmcnt(0)
	v_mfma_f32_16x16x32_bf16 v[66:69], v[70:73], v[10:13], v[66:69]
	v_mul_f32_e32 v145, v98, v126
	v_mul_f32_e32 v147, v96, v126
	v_cmp_ne_u32_e64 s[20:21], s62, v107
	v_mul_f32_e32 v144, v97, v130
	v_mul_f32_e32 v146, v95, v130
	v_mul_f32_e32 v149, v94, v126
	v_cmp_ne_u32_e64 s[22:23], s62, v108
	v_mul_f32_e32 v126, v92, v126
	v_cmp_ne_u32_e64 s[24:25], s62, v109
	v_cndmask_b32_e64 v123, 2.0, v145, s[18:19]
	v_cmp_lt_i32_e64 s[12:13], 0, v125
	v_cndmask_b32_e64 v136, 2.0, v147, s[20:21]
	v_cmp_lt_i32_e64 s[14:15], 1, v125
	v_mul_f32_e32 v148, v93, v130
	v_mul_f32_e32 v130, v91, v130
	v_cndmask_b32_e64 v137, 2.0, v149, s[22:23]
	v_cmp_lt_i32_e64 s[16:17], 2, v125
	v_cndmask_b32_e64 v126, 2.0, v126, s[24:25]
	v_cmp_lt_i32_e64 s[18:19], 3, v125
	v_cndmask_b32_e64 v120, v123, v144, s[12:13]
	v_cndmask_b32_e64 v121, v136, v146, s[14:15]
	v_cndmask_b32_e64 v74, v137, v148, s[16:17]
	v_cndmask_b32_e64 v75, v126, v130, s[18:19]
	v_mul_f32_e32 v66, v120, v66
	v_mul_f32_e32 v67, v121, v67
	v_mul_f32_e32 v68, v74, v68
	v_mul_f32_e32 v69, v75, v69
	v_cvt_pk_bf16_f32 v66, v66, v67
	v_cvt_pk_bf16_f32 v67, v68, v69
	ds_write_b64 v100, v[66:67] offset:53312
	ds_read_b128 v[66:69], v83 offset:13056
	ds_read_b128 v[70:73], v83 offset:13120
	s_waitcnt lgkmcnt(1)
	v_mfma_f32_16x16x32_bf16 v[66:69], v[66:69], v[30:33], 0
	ds_read_b128 v[74:77], v83 offset:13184
	v_cvt_f32_i32_e32 v128, v128
	v_cvt_f32_i32_e32 v131, v127
	s_waitcnt lgkmcnt(1)
	v_mfma_f32_16x16x32_bf16 v[66:69], v[70:73], v[22:25], v[66:69]
	ds_read_b128 v[70:73], v83 offset:13248
	v_mul_f32_e32 v128, v99, v128
	v_mul_f32_e32 v131, v90, v131
	s_waitcnt lgkmcnt(1)
	v_mfma_f32_16x16x32_bf16 v[66:69], v[74:77], v[14:17], v[66:69]
	v_exp_f32_e32 v128, v128
	v_exp_f32_e32 v131, v131
	v_cmp_gt_i32_e64 s[26:27], 0, v127
	s_waitcnt lgkmcnt(0)
	v_mfma_f32_16x16x32_bf16 v[66:69], v[70:73], v[10:13], v[66:69]
	v_mul_f32_e32 v151, v98, v128
	v_mul_f32_e32 v153, v96, v128
	v_cmp_ne_u32_e64 s[28:29], s62, v104
	v_mul_f32_e32 v150, v97, v131
	v_mul_f32_e32 v152, v95, v131
	v_mul_f32_e32 v155, v94, v128
	v_cmp_ne_u32_e64 s[30:31], s62, v105
	v_mul_f32_e32 v128, v92, v128
	v_cmp_ne_u32_e64 s[34:35], s62, v106
	v_cndmask_b32_e64 v125, 2.0, v151, s[26:27]
	v_cmp_lt_i32_e64 s[20:21], 0, v127
	v_cndmask_b32_e64 v139, 2.0, v153, s[28:29]
	v_cmp_lt_i32_e64 s[22:23], 1, v127
	v_mul_f32_e32 v154, v93, v131
	v_mul_f32_e32 v131, v91, v131
	v_cndmask_b32_e64 v141, 2.0, v155, s[30:31]
	v_cmp_lt_i32_e64 s[24:25], 2, v127
	v_cndmask_b32_e64 v116, 2.0, v128, s[34:35]
	v_cmp_lt_i32_e64 s[26:27], 3, v127
	v_cndmask_b32_e64 v117, v125, v150, s[20:21]
	v_cndmask_b32_e64 v74, v139, v152, s[22:23]
	v_cndmask_b32_e64 v75, v141, v154, s[24:25]
	v_cndmask_b32_e64 v76, v116, v131, s[26:27]
	v_mul_f32_e32 v66, v117, v66
	v_mul_f32_e32 v67, v74, v67
	v_mul_f32_e32 v68, v75, v68
	v_mul_f32_e32 v69, v76, v69
	v_cvt_pk_bf16_f32 v66, v66, v67
	v_cvt_pk_bf16_f32 v67, v68, v69
	ds_write_b64 v100, v[66:67] offset:53344
	v_add_u32_e32 v79, v102, v78
	s_waitcnt lgkmcnt(0)
	ds_read_b128 v[66:69], v79 offset:53248
	ds_read_b128 v[70:73], v79 offset:53312
	ds_read_b64_tr_b16 v[76:77], v81 offset:18496
	ds_read_b64_tr_b16 v[74:75], v81 offset:17408
	ds_read_b64_tr_b16 v[116:117], v81 offset:17440
	ds_read_b64_tr_b16 v[120:121], v81 offset:17472
	ds_read_b64_tr_b16 v[124:125], v81 offset:17504
	ds_read_b64_tr_b16 v[118:119], v81 offset:18528
	ds_read_b64_tr_b16 v[122:123], v81 offset:18560
	ds_read_b64_tr_b16 v[126:127], v81 offset:18592
	s_waitcnt lgkmcnt(6)
	v_mfma_f32_16x16x32_bf16 v[46:49], v[66:69], v[74:77], v[46:49]
	ds_read_b64_tr_b16 v[74:75], v81 offset:17536
	ds_read_b64_tr_b16 v[76:77], v81 offset:18624
	s_add_i32 s63, s63, 64
	s_sub_i32 s62, s62, 64
	s_waitcnt lgkmcnt(4)
	v_mfma_f32_16x16x32_bf16 v[42:45], v[66:69], v[116:119], v[42:45]
	v_lshl_add_u64 v[86:87], v[86:87], 0, s[64:65]
	s_cmpk_eq_i32 s62, 0xff40
	v_lshl_add_u64 v[88:89], v[88:89], 0, s[64:65]
	s_waitcnt lgkmcnt(3)
	v_mfma_f32_16x16x32_bf16 v[38:41], v[66:69], v[120:123], v[38:41]
	ds_read_b64_tr_b16 v[116:117], v81 offset:17568
	ds_read_b64_tr_b16 v[120:121], v81 offset:17600
	ds_read_b64_tr_b16 v[128:129], v81 offset:17632
	ds_read_b64_tr_b16 v[118:119], v81 offset:18656
	ds_read_b64_tr_b16 v[122:123], v81 offset:18688
	ds_read_b64_tr_b16 v[130:131], v81 offset:18720
	s_waitcnt lgkmcnt(6)
	v_mfma_f32_16x16x32_bf16 v[26:29], v[66:69], v[74:77], v[26:29]
	ds_read_b64_tr_b16 v[74:75], v81 offset:26112
	ds_read_b64_tr_b16 v[76:77], v81 offset:27200
	v_mfma_f32_16x16x32_bf16 v[34:37], v[66:69], v[124:127], v[34:37]
	s_waitcnt lgkmcnt(4)
	v_mfma_f32_16x16x32_bf16 v[18:21], v[66:69], v[116:119], v[18:21]
	s_waitcnt lgkmcnt(3)
	v_mfma_f32_16x16x32_bf16 v[2:5], v[66:69], v[120:123], v[2:5]
	ds_read_b64_tr_b16 v[116:117], v81 offset:26144
	ds_read_b64_tr_b16 v[120:121], v81 offset:26176
	ds_read_b64_tr_b16 v[124:125], v81 offset:26208
	ds_read_b64_tr_b16 v[118:119], v81 offset:27232
	ds_read_b64_tr_b16 v[122:123], v81 offset:27264
	ds_read_b64_tr_b16 v[126:127], v81 offset:27296
	s_waitcnt lgkmcnt(8)
	v_mfma_f32_16x16x32_bf16 v[6:9], v[66:69], v[128:131], v[6:9]
	ds_read_b64_tr_b16 v[66:67], v81 offset:26240
	ds_read_b64_tr_b16 v[68:69], v81 offset:27328
	s_waitcnt lgkmcnt(8)
	v_mfma_f32_16x16x32_bf16 v[46:49], v[70:73], v[74:77], v[46:49]
	s_waitcnt lgkmcnt(4)
	v_mfma_f32_16x16x32_bf16 v[42:45], v[70:73], v[116:119], v[42:45]
	s_waitcnt lgkmcnt(3)
	v_mfma_f32_16x16x32_bf16 v[38:41], v[70:73], v[120:123], v[38:41]
	ds_read_b64_tr_b16 v[74:75], v81 offset:26272
	ds_read_b64_tr_b16 v[116:117], v81 offset:26304
	ds_read_b64_tr_b16 v[120:121], v81 offset:26336
	ds_read_b64_tr_b16 v[76:77], v81 offset:27360
	ds_read_b64_tr_b16 v[118:119], v81 offset:27392
	ds_read_b64_tr_b16 v[122:123], v81 offset:27424
	s_waitcnt lgkmcnt(8)
	v_mfma_f32_16x16x32_bf16 v[34:37], v[70:73], v[124:127], v[34:37]
	s_waitcnt lgkmcnt(6)
	v_mfma_f32_16x16x32_bf16 v[26:29], v[70:73], v[66:69], v[26:29]
	s_waitcnt lgkmcnt(2)
	v_mfma_f32_16x16x32_bf16 v[18:21], v[70:73], v[74:77], v[18:21]
	s_waitcnt lgkmcnt(1)
	v_mfma_f32_16x16x32_bf16 v[2:5], v[70:73], v[116:119], v[2:5]
	s_waitcnt lgkmcnt(0)
	v_mfma_f32_16x16x32_bf16 v[6:9], v[70:73], v[120:123], v[6:9]
	s_cbranch_scc0 .LBB0_388
	s_barrier
	s_waitcnt vmcnt(3)
	ds_write_b128 v82, v[50:53]
	s_waitcnt vmcnt(2)
	ds_write_b128 v82, v[54:57] offset:17408
	s_waitcnt vmcnt(1)
	ds_write_b128 v80, v[58:61]
	s_waitcnt vmcnt(0)
	ds_write_b128 v80, v[62:65] offset:17408
	s_waitcnt lgkmcnt(0)
	s_barrier
	ds_read_b128 v[50:53], v83
	ds_read_b128 v[54:57], v83 offset:64
	ds_read_b128 v[58:61], v83 offset:128
	ds_read_b128 v[62:65], v83 offset:192
	s_waitcnt lgkmcnt(3)
	v_mfma_f32_16x16x32_bf16 v[50:53], v[50:53], v[30:33], 0
	v_sub_u32_e32 v67, 0xc0, v101
	v_add_u32_e32 v66, 0xffffff40, v101
	v_cvt_f32_i32_e32 v66, v66
	s_waitcnt lgkmcnt(2)
	v_mfma_f32_16x16x32_bf16 v[50:53], v[54:57], v[22:25], v[50:53]
	v_cvt_f32_i32_e32 v54, v67
	s_movk_i32 s5, 0xc0
	v_mul_f32_e32 v55, v90, v66
	s_waitcnt lgkmcnt(1)
	v_mfma_f32_16x16x32_bf16 v[50:53], v[58:61], v[14:17], v[50:53]
	v_mul_f32_e32 v54, v99, v54
	v_exp_f32_e32 v54, v54
	v_exp_f32_e32 v55, v55
	s_waitcnt lgkmcnt(0)
	v_mfma_f32_16x16x32_bf16 v[50:53], v[62:65], v[10:13], v[50:53]
	v_cmp_ne_u32_e32 vcc, s5, v101
	v_mul_f32_e32 v57, v54, v98
	v_mul_f32_e32 v56, v55, v97
	v_cndmask_b32_e32 v57, 2.0, v57, vcc
	v_cmp_lt_i32_e32 vcc, s5, v101
	s_movk_i32 s5, 0xc1
	v_sub_u32_e32 v67, 0xd0, v101
	v_cndmask_b32_e32 v56, v57, v56, vcc
	v_mul_f32_e32 v57, v96, v54
	v_cmp_ne_u32_e32 vcc, s5, v101
	v_mul_f32_e32 v50, v56, v50
	v_mul_f32_e32 v56, v95, v55
	v_cndmask_b32_e32 v57, 2.0, v57, vcc
	v_cmp_lt_i32_e32 vcc, s5, v101
	s_movk_i32 s5, 0xc2
	v_add_u32_e32 v66, 0xffffff30, v101
	v_cndmask_b32_e32 v56, v57, v56, vcc
	v_mul_f32_e32 v57, v54, v94
	v_cmp_ne_u32_e32 vcc, s5, v101
	v_mul_f32_e32 v51, v56, v51
	v_mul_f32_e32 v56, v55, v93
	v_cndmask_b32_e32 v57, 2.0, v57, vcc
	v_cmp_lt_i32_e32 vcc, s5, v101
	s_movk_i32 s5, 0xc3
	v_mul_f32_e32 v54, v54, v92
	v_cndmask_b32_e32 v56, v57, v56, vcc
	v_cmp_ne_u32_e32 vcc, s5, v101
	v_mul_f32_e32 v55, v55, v91
	v_mul_f32_e32 v52, v56, v52
	v_cndmask_b32_e32 v54, 2.0, v54, vcc
	v_cmp_lt_i32_e32 vcc, s5, v101
	v_cvt_pk_bf16_f32 v50, v50, v51
	v_cvt_f32_i32_e32 v66, v66
	s_movk_i32 s5, 0xd0
	v_cndmask_b32_e32 v54, v54, v55, vcc
	v_mul_f32_e32 v53, v54, v53
	v_cvt_pk_bf16_f32 v51, v52, v53
	ds_write_b64 v100, v[50:51] offset:53248
	ds_read_b128 v[50:53], v83 offset:4352
	ds_read_b128 v[54:57], v83 offset:4416
	ds_read_b128 v[58:61], v83 offset:4480
	ds_read_b128 v[62:65], v83 offset:4544
	s_waitcnt lgkmcnt(3)
	v_mfma_f32_16x16x32_bf16 v[50:53], v[50:53], v[30:33], 0
	v_cmp_ne_u32_e32 vcc, s5, v101
	s_or_b32 s0, s1, s0
	s_add_i32 s0, s0, s3
	s_waitcnt lgkmcnt(2)
	v_mfma_f32_16x16x32_bf16 v[50:53], v[54:57], v[22:25], v[50:53]
	v_cvt_f32_i32_e32 v54, v67
	v_mul_f32_e32 v55, v90, v66
	v_exp_f32_e32 v55, v55
	s_waitcnt lgkmcnt(1)
	v_mfma_f32_16x16x32_bf16 v[50:53], v[58:61], v[14:17], v[50:53]
	v_mul_f32_e32 v54, v99, v54
	v_exp_f32_e32 v54, v54
	v_mul_f32_e32 v56, v55, v97
	s_waitcnt lgkmcnt(0)
	v_mfma_f32_16x16x32_bf16 v[50:53], v[62:65], v[10:13], v[50:53]
	v_sub_u32_e32 v67, 0xe0, v101
	v_mul_f32_e32 v57, v54, v98
	v_cndmask_b32_e32 v57, 2.0, v57, vcc
	v_cmp_lt_i32_e32 vcc, s5, v101
	s_movk_i32 s5, 0xd1
	v_add_u32_e32 v66, 0xffffff20, v101
	v_cndmask_b32_e32 v56, v57, v56, vcc
	v_mul_f32_e32 v57, v96, v54
	v_cmp_ne_u32_e32 vcc, s5, v101
	v_mul_f32_e32 v50, v56, v50
	v_mul_f32_e32 v56, v95, v55
	v_cndmask_b32_e32 v57, 2.0, v57, vcc
	v_cmp_lt_i32_e32 vcc, s5, v101
	s_movk_i32 s5, 0xd2
	v_cvt_f32_i32_e32 v66, v66
	v_cndmask_b32_e32 v56, v57, v56, vcc
	v_mul_f32_e32 v57, v54, v94
	v_cmp_ne_u32_e32 vcc, s5, v101
	v_mul_f32_e32 v51, v56, v51
	v_mul_f32_e32 v56, v55, v93
	v_cndmask_b32_e32 v57, 2.0, v57, vcc
	v_cmp_lt_i32_e32 vcc, s5, v101
	s_movk_i32 s5, 0xd3
	v_mul_f32_e32 v54, v54, v92
	v_cndmask_b32_e32 v56, v57, v56, vcc
	v_cmp_ne_u32_e32 vcc, s5, v101
	v_mul_f32_e32 v55, v55, v91
	v_mul_f32_e32 v52, v56, v52
	v_cndmask_b32_e32 v54, 2.0, v54, vcc
	v_cmp_lt_i32_e32 vcc, s5, v101
	v_cvt_pk_bf16_f32 v50, v50, v51
	s_movk_i32 s5, 0xe0
	s_mov_b32 s7, 0
	v_cndmask_b32_e32 v54, v54, v55, vcc
	v_mul_f32_e32 v53, v54, v53
	v_cvt_pk_bf16_f32 v51, v52, v53
	ds_write_b64 v100, v[50:51] offset:53280
	ds_read_b128 v[50:53], v83 offset:8704
	ds_read_b128 v[54:57], v83 offset:8768
	ds_read_b128 v[58:61], v83 offset:8832
	ds_read_b128 v[62:65], v83 offset:8896
	s_waitcnt lgkmcnt(3)
	v_mfma_f32_16x16x32_bf16 v[50:53], v[50:53], v[30:33], 0
	v_cmp_ne_u32_e32 vcc, s5, v101
	s_lshl_b32 s6, s4, 1
	s_waitcnt lgkmcnt(2)
	v_mfma_f32_16x16x32_bf16 v[50:53], v[54:57], v[22:25], v[50:53]
	v_cvt_f32_i32_e32 v54, v67
	v_mul_f32_e32 v55, v90, v66
	v_exp_f32_e32 v55, v55
	s_waitcnt lgkmcnt(1)
	v_mfma_f32_16x16x32_bf16 v[50:53], v[58:61], v[14:17], v[50:53]
	v_mul_f32_e32 v54, v99, v54
	v_exp_f32_e32 v54, v54
	v_mul_f32_e32 v56, v55, v97
	s_waitcnt lgkmcnt(0)
	v_mfma_f32_16x16x32_bf16 v[50:53], v[62:65], v[10:13], v[50:53]
	v_mul_f32_e32 v57, v54, v98
	v_cndmask_b32_e32 v57, 2.0, v57, vcc
	v_cmp_lt_i32_e32 vcc, s5, v101
	s_movk_i32 s5, 0xe1
	s_nop 0
	v_cndmask_b32_e32 v56, v57, v56, vcc
	v_mul_f32_e32 v57, v96, v54
	v_cmp_ne_u32_e32 vcc, s5, v101
	v_mul_f32_e32 v50, v56, v50
	v_mul_f32_e32 v56, v95, v55
	v_cndmask_b32_e32 v57, 2.0, v57, vcc
	v_cmp_lt_i32_e32 vcc, s5, v101
	s_movk_i32 s5, 0xe2
	s_nop 0
	v_cndmask_b32_e32 v56, v57, v56, vcc
	v_mul_f32_e32 v57, v54, v94
	v_cmp_ne_u32_e32 vcc, s5, v101
	v_mul_f32_e32 v51, v56, v51
	v_mul_f32_e32 v56, v55, v93
	v_cndmask_b32_e32 v57, 2.0, v57, vcc
	v_cmp_lt_i32_e32 vcc, s5, v101
	s_movk_i32 s5, 0xe3
	v_mul_f32_e32 v54, v54, v92
	v_cndmask_b32_e32 v56, v57, v56, vcc
	v_cmp_ne_u32_e32 vcc, s5, v101
	v_mul_f32_e32 v55, v55, v91
	v_mul_f32_e32 v52, v56, v52
	v_cndmask_b32_e32 v54, 2.0, v54, vcc
	v_cmp_lt_i32_e32 vcc, s5, v101
	v_cvt_pk_bf16_f32 v50, v50, v51
	s_movk_i32 s5, 0xf0
	s_nop 0
	v_cndmask_b32_e32 v54, v54, v55, vcc
	v_mul_f32_e32 v53, v54, v53
	v_cvt_pk_bf16_f32 v51, v52, v53
	ds_write_b64 v100, v[50:51] offset:53312
	ds_read_b128 v[50:53], v83 offset:13056
	ds_read_b128 v[54:57], v83 offset:13120
	ds_read_b128 v[58:61], v83 offset:13184
	ds_read_b128 v[62:65], v83 offset:13248
	s_waitcnt lgkmcnt(3)
	v_mfma_f32_16x16x32_bf16 v[30:33], v[50:53], v[30:33], 0
	v_sub_u32_e32 v51, 0xf0, v101
	v_add_u32_e32 v50, 0xffffff10, v101
	v_cvt_f32_i32_e32 v50, v50
	s_waitcnt lgkmcnt(2)
	v_mfma_f32_16x16x32_bf16 v[22:25], v[54:57], v[22:25], v[30:33]
	v_cmp_ne_u32_e32 vcc, s5, v101
	s_nop 1
	v_cvt_f32_i32_e32 v30, v51
	s_waitcnt lgkmcnt(1)
	v_mfma_f32_16x16x32_bf16 v[14:17], v[58:61], v[14:17], v[22:25]
	v_mul_f32_e32 v31, v90, v50
	v_mul_f32_e32 v30, v99, v30
	s_nop 0
	v_exp_f32_e32 v23, v30
	v_exp_f32_e32 v22, v31
	s_waitcnt lgkmcnt(0)
	v_mfma_f32_16x16x32_bf16 v[10:13], v[62:65], v[10:13], v[14:17]
	s_nop 2
	v_mul_f32_e32 v15, v23, v98
	v_mul_f32_e32 v14, v22, v97
	v_cndmask_b32_e32 v15, 2.0, v15, vcc
	v_cmp_lt_i32_e32 vcc, s5, v101
	s_movk_i32 s5, 0xf1
	s_nop 0
	v_cndmask_b32_e32 v14, v15, v14, vcc
	v_mul_f32_e32 v15, v96, v23
	v_cmp_ne_u32_e32 vcc, s5, v101
	v_mul_f32_e32 v10, v14, v10
	v_mul_f32_e32 v14, v95, v22
	v_cndmask_b32_e32 v15, 2.0, v15, vcc
	v_cmp_lt_i32_e32 vcc, s5, v101
	s_movk_i32 s5, 0xf2
	s_nop 0
	v_cndmask_b32_e32 v14, v15, v14, vcc
	v_mul_f32_e32 v15, v23, v94
	v_cmp_ne_u32_e32 vcc, s5, v101
	v_mul_f32_e32 v11, v14, v11
	v_mul_f32_e32 v14, v22, v93
	v_cndmask_b32_e32 v15, 2.0, v15, vcc
	v_cmp_lt_i32_e32 vcc, s5, v101
	s_movk_i32 s5, 0xf3
	v_cvt_pk_bf16_f32 v10, v10, v11
	s_nop 0
	v_cndmask_b32_e32 v14, v15, v14, vcc
	v_mul_f32_e32 v15, v23, v92
	v_cmp_ne_u32_e32 vcc, s5, v101
	v_mul_f32_e32 v12, v14, v12
	v_mul_f32_e32 v14, v22, v91
	v_cndmask_b32_e32 v15, 2.0, v15, vcc
	v_cmp_lt_i32_e32 vcc, s5, v101
	s_nop 1
	v_cndmask_b32_e32 v14, v15, v14, vcc
	v_mul_f32_e32 v13, v14, v13
	v_cvt_pk_bf16_f32 v11, v12, v13
	ds_write_b64 v100, v[10:11] offset:53344
	s_waitcnt lgkmcnt(0)
	ds_read_b128 v[54:57], v79 offset:53248
	ds_read_b128 v[50:53], v79 offset:53312
	ds_read_b64_tr_b16 v[12:13], v81 offset:18496
	ds_read_b64_tr_b16 v[10:11], v81 offset:17408
	ds_read_b64_tr_b16 v[14:15], v81 offset:17440
	ds_read_b64_tr_b16 v[58:59], v81 offset:17472
	ds_read_b64_tr_b16 v[62:63], v81 offset:17504
	ds_read_b64_tr_b16 v[16:17], v81 offset:18528
	ds_read_b64_tr_b16 v[60:61], v81 offset:18560
	ds_read_b64_tr_b16 v[64:65], v81 offset:18592
	s_waitcnt lgkmcnt(6)
	v_mfma_f32_16x16x32_bf16 v[10:13], v[54:57], v[10:13], v[46:49]
	ds_read_b64_tr_b16 v[24:25], v81 offset:27200
	ds_read_b64_tr_b16 v[22:23], v81 offset:26112
	s_nop 0
	ds_read_b64_tr_b16 v[46:47], v81 offset:26144
	ds_read_b64_tr_b16 v[66:67], v81 offset:26176
	ds_read_b64_tr_b16 v[70:71], v81 offset:26208
	ds_read_b64_tr_b16 v[48:49], v81 offset:27232
	ds_read_b64_tr_b16 v[68:69], v81 offset:27264
	ds_read_b64_tr_b16 v[72:73], v81 offset:27296
	s_waitcnt lgkmcnt(6)
	v_mfma_f32_16x16x32_bf16 v[30:33], v[50:53], v[22:25], v[10:13]
	v_mfma_f32_16x16x32_bf16 v[10:13], v[54:57], v[14:17], v[42:45]
	s_waitcnt lgkmcnt(2)
	v_mfma_f32_16x16x32_bf16 v[22:25], v[50:53], v[46:49], v[10:13]
	v_mfma_f32_16x16x32_bf16 v[10:13], v[54:57], v[58:61], v[38:41]
	s_waitcnt lgkmcnt(1)
	v_mfma_f32_16x16x32_bf16 v[14:17], v[50:53], v[66:69], v[10:13]
	v_mfma_f32_16x16x32_bf16 v[10:13], v[54:57], v[62:65], v[34:37]
	s_nop 2
	ds_read_b64_tr_b16 v[36:37], v81 offset:18624
	ds_read_b64_tr_b16 v[34:35], v81 offset:17536
	ds_read_b64_tr_b16 v[38:39], v81 offset:17568
	ds_read_b64_tr_b16 v[42:43], v81 offset:17600
	ds_read_b64_tr_b16 v[46:47], v81 offset:17632
	ds_read_b64_tr_b16 v[40:41], v81 offset:18656
	ds_read_b64_tr_b16 v[44:45], v81 offset:18688
	ds_read_b64_tr_b16 v[48:49], v81 offset:18720
	s_waitcnt lgkmcnt(6)
	v_mfma_f32_16x16x32_bf16 v[26:29], v[54:57], v[34:37], v[26:29]
	ds_read_b64_tr_b16 v[36:37], v81 offset:27328
	ds_read_b64_tr_b16 v[34:35], v81 offset:26240
	ds_read_b64_tr_b16 v[58:59], v81 offset:26272
	ds_read_b64_tr_b16 v[62:63], v81 offset:26304
	ds_read_b64_tr_b16 v[66:67], v81 offset:26336
	ds_read_b64_tr_b16 v[60:61], v81 offset:27360
	ds_read_b64_tr_b16 v[64:65], v81 offset:27392
	ds_read_b64_tr_b16 v[68:69], v81 offset:27424
	s_waitcnt lgkmcnt(6)
	v_mfma_f32_16x16x32_bf16 v[26:29], v[50:53], v[34:37], v[26:29]
	v_and_b32_e32 v34, 15, v1
	v_ashrrev_i32_e32 v1, 2, v1
	v_and_b32_e32 v1, -4, v1
	v_mfma_f32_16x16x32_bf16 v[18:21], v[54:57], v[38:41], v[18:21]
	v_add_u32_e32 v36, s0, v1
	s_movk_i32 s0, 0x1400
	v_mov_b64_e32 v[40:41], s[68:69]
	v_lshlrev_b32_e32 v38, 1, v34
	v_mad_i64_i32 v[34:35], s[4:5], v36, s0, v[40:41]
	v_mov_b32_e32 v39, 0
	v_lshl_add_u64 v[34:35], v[34:35], 0, s[6:7]
	s_waitcnt lgkmcnt(2)
	v_mfma_f32_16x16x32_bf16 v[18:21], v[50:53], v[58:61], v[18:21]
	v_lshl_add_u64 v[58:59], v[34:35], 0, v[38:39]
	v_add_f32_e32 v1, 0, v30
	v_mfma_f32_16x16x32_bf16 v[2:5], v[54:57], v[42:45], v[2:5]
	v_add_f32_e32 v1, v1, v22
	v_mfma_f32_16x16x32_bf16 v[6:9], v[54:57], v[46:49], v[6:9]
	v_mfma_f32_16x16x32_bf16 v[10:13], v[50:53], v[70:73], v[10:13]
	v_add_f32_e32 v1, v1, v14
	s_add_u32 s4, s60, s6
	s_addc_u32 s5, s61, 0
	s_waitcnt lgkmcnt(1)
	v_mfma_f32_16x16x32_bf16 v[2:5], v[50:53], v[62:65], v[2:5]
	v_lshl_add_u64 v[34:35], s[4:5], 0, v[38:39]
	s_nop 1
	v_add_f32_e32 v1, v1, v10
	v_add_f32_e32 v1, v1, v26
	s_waitcnt lgkmcnt(0)
	v_mfma_f32_16x16x32_bf16 v[6:9], v[50:53], v[66:69], v[6:9]
	v_and_b32_e32 v160, 63, v0
	v_and_b32_e32 v161, 15, v160
	v_lshrrev_b32_e32 v162, 4, v160
	v_lshrrev_b32_e32 v168, 2, v160
	v_and_b32_e32 v169, 3, v160
	v_readfirstlane_b32 s99, v36
	v_readfirstlane_b32 s98, v0
	s_lshr_b32 s98, s98, 6
	s_mul_i32 s98, s98, 0x1200
	s_add_i32 s98, s98, 0xd000
	s_add_u32 s100, s68, s6
	s_addc_u32 s101, s69, 0
	v_add_u32_e32 v171, s99, v168
	v_mul_u32_u24_e32 v172, 0x1400, v171
	v_lshl_add_u32 v172, v169, 5, v172
	v_add_u32_e32 v172, 0xc00, v172
	global_load_dwordx4 v[200:203], v172, s[100:101]
	global_load_dwordx4 v[204:207], v172, s[100:101] offset:16
	global_load_dwordx4 v[224:227], v172, s[100:101] offset:128
	global_load_dwordx4 v[228:231], v172, s[100:101] offset:144
	v_lshlrev_b32_e32 v173, 11, v171
	v_lshl_add_u32 v173, v169, 5, v173
	v_lshlrev_b32_e32 v167, 2, v162
	v_mul_u32_u24_e32 v167, 0x110, v167
	v_lshl_add_u32 v167, v161, 2, v167
	v_add_u32_e32 v167, s98, v167
	v_mul_u32_u24_e32 v170, 0x110, v168
	v_lshl_add_u32 v170, v169, 6, v170
	v_add_u32_e32 v170, s98, v170
	v_mov_b32_e32 v163, 0x3727c5ac
	s_nop 7
	v_add_f32_e32 v164, 0, v30
	v_add_f32_e32 v165, 0, v31
	v_add_f32_e32 v166, 0, v32
	v_add_f32_e32 v174, 0, v33
	v_add_f32_e32 v164, v164, v22
	v_add_f32_e32 v165, v165, v23
	v_add_f32_e32 v166, v166, v24
	v_add_f32_e32 v174, v174, v25
	v_add_f32_e32 v164, v164, v14
	v_add_f32_e32 v165, v165, v15
	v_add_f32_e32 v166, v166, v16
	v_add_f32_e32 v174, v174, v17
	v_add_f32_e32 v164, v164, v10
	v_add_f32_e32 v165, v165, v11
	v_add_f32_e32 v166, v166, v12
	v_add_f32_e32 v174, v174, v13
	v_add_f32_e32 v164, v164, v26
	v_add_f32_e32 v165, v165, v27
	v_add_f32_e32 v166, v166, v28
	v_add_f32_e32 v174, v174, v29
	v_add_f32_e32 v164, v164, v18
	v_add_f32_e32 v165, v165, v19
	v_add_f32_e32 v166, v166, v20
	v_add_f32_e32 v174, v174, v21
	v_add_f32_e32 v164, v164, v2
	v_add_f32_e32 v165, v165, v3
	v_add_f32_e32 v166, v166, v4
	v_add_f32_e32 v174, v174, v5
	v_add_f32_e32 v164, v164, v6
	v_add_f32_e32 v165, v165, v7
	v_add_f32_e32 v166, v166, v8
	v_add_f32_e32 v174, v174, v9
	v_add_f32_dpp v164, v164, v164 quad_perm:[1,0,3,2] row_mask:0xf bank_mask:0xf bound_ctrl:1
	v_add_f32_dpp v165, v165, v165 quad_perm:[1,0,3,2] row_mask:0xf bank_mask:0xf bound_ctrl:1
	v_add_f32_dpp v166, v166, v166 quad_perm:[1,0,3,2] row_mask:0xf bank_mask:0xf bound_ctrl:1
	v_add_f32_dpp v174, v174, v174 quad_perm:[1,0,3,2] row_mask:0xf bank_mask:0xf bound_ctrl:1
	v_add_f32_dpp v164, v164, v164 quad_perm:[2,3,0,1] row_mask:0xf bank_mask:0xf bound_ctrl:1
	v_add_f32_dpp v165, v165, v165 quad_perm:[2,3,0,1] row_mask:0xf bank_mask:0xf bound_ctrl:1
	v_add_f32_dpp v166, v166, v166 quad_perm:[2,3,0,1] row_mask:0xf bank_mask:0xf bound_ctrl:1
	v_add_f32_dpp v174, v174, v174 quad_perm:[2,3,0,1] row_mask:0xf bank_mask:0xf bound_ctrl:1
	v_add_f32_dpp v164, v164, v164 row_half_mirror row_mask:0xf bank_mask:0xf bound_ctrl:1
	v_add_f32_dpp v165, v165, v165 row_half_mirror row_mask:0xf bank_mask:0xf bound_ctrl:1
	v_add_f32_dpp v166, v166, v166 row_half_mirror row_mask:0xf bank_mask:0xf bound_ctrl:1
	v_add_f32_dpp v174, v174, v174 row_half_mirror row_mask:0xf bank_mask:0xf bound_ctrl:1
	v_add_f32_dpp v164, v164, v164 row_mirror row_mask:0xf bank_mask:0xf bound_ctrl:1
	v_add_f32_dpp v165, v165, v165 row_mirror row_mask:0xf bank_mask:0xf bound_ctrl:1
	v_add_f32_dpp v166, v166, v166 row_mirror row_mask:0xf bank_mask:0xf bound_ctrl:1
	v_add_f32_dpp v174, v174, v174 row_mirror row_mask:0xf bank_mask:0xf bound_ctrl:1
	v_fmamk_f32 v22, v164, 0xbc000000, v22
	v_fmamk_f32 v23, v165, 0xbc000000, v23
	v_fmamk_f32 v24, v166, 0xbc000000, v24
	v_fmamk_f32 v25, v174, 0xbc000000, v25
	v_fmamk_f32 v30, v164, 0xbc000000, v30
	v_fmamk_f32 v31, v165, 0xbc000000, v31
	v_fmamk_f32 v32, v166, 0xbc000000, v32
	v_fmamk_f32 v33, v174, 0xbc000000, v33
	v_mul_f32_e32 v175, v22, v22
	v_mul_f32_e32 v176, v23, v23
	v_mul_f32_e32 v177, v24, v24
	v_mul_f32_e32 v178, v25, v25
	v_fmac_f32_e32 v175, v30, v30
	v_fmac_f32_e32 v176, v31, v31
	v_fmac_f32_e32 v177, v32, v32
	v_fmac_f32_e32 v178, v33, v33
	v_fmamk_f32 v14, v164, 0xbc000000, v14
	v_fmamk_f32 v15, v165, 0xbc000000, v15
	v_fmamk_f32 v16, v166, 0xbc000000, v16
	v_fmamk_f32 v17, v174, 0xbc000000, v17
	v_fmac_f32_e32 v175, v14, v14
	v_fmac_f32_e32 v176, v15, v15
	v_fmac_f32_e32 v177, v16, v16
	v_fmac_f32_e32 v178, v17, v17
	v_fmamk_f32 v10, v164, 0xbc000000, v10
	v_fmamk_f32 v11, v165, 0xbc000000, v11
	v_fmamk_f32 v12, v166, 0xbc000000, v12
	v_fmamk_f32 v13, v174, 0xbc000000, v13
	v_fmac_f32_e32 v175, v10, v10
	v_fmac_f32_e32 v176, v11, v11
	v_fmac_f32_e32 v177, v12, v12
	v_fmac_f32_e32 v178, v13, v13
	v_fmamk_f32 v26, v164, 0xbc000000, v26
	v_fmamk_f32 v27, v165, 0xbc000000, v27
	v_fmamk_f32 v28, v166, 0xbc000000, v28
	v_fmamk_f32 v29, v174, 0xbc000000, v29
	v_fmac_f32_e32 v175, v26, v26
	v_fmac_f32_e32 v176, v27, v27
	v_fmac_f32_e32 v177, v28, v28
	v_fmac_f32_e32 v178, v29, v29
	v_fmamk_f32 v18, v164, 0xbc000000, v18
	v_fmamk_f32 v19, v165, 0xbc000000, v19
	v_fmamk_f32 v20, v166, 0xbc000000, v20
	v_fmamk_f32 v21, v174, 0xbc000000, v21
	v_fmac_f32_e32 v175, v18, v18
	v_fmac_f32_e32 v176, v19, v19
	v_fmac_f32_e32 v177, v20, v20
	v_fmac_f32_e32 v178, v21, v21
	v_fmamk_f32 v2, v164, 0xbc000000, v2
	v_fmamk_f32 v3, v165, 0xbc000000, v3
	v_fmamk_f32 v4, v166, 0xbc000000, v4
	v_fmamk_f32 v5, v174, 0xbc000000, v5
	v_fmac_f32_e32 v175, v2, v2
	v_fmac_f32_e32 v176, v3, v3
	v_fmac_f32_e32 v177, v4, v4
	v_fmac_f32_e32 v178, v5, v5
	v_fmamk_f32 v6, v164, 0xbc000000, v6
	v_fmamk_f32 v7, v165, 0xbc000000, v7
	v_fmamk_f32 v8, v166, 0xbc000000, v8
	v_fmamk_f32 v9, v174, 0xbc000000, v9
	v_fmac_f32_e32 v175, v6, v6
	v_fmac_f32_e32 v176, v7, v7
	v_fmac_f32_e32 v177, v8, v8
	v_fmac_f32_e32 v178, v9, v9
	v_add_f32_dpp v175, v175, v175 quad_perm:[1,0,3,2] row_mask:0xf bank_mask:0xf bound_ctrl:1
	v_add_f32_dpp v176, v176, v176 quad_perm:[1,0,3,2] row_mask:0xf bank_mask:0xf bound_ctrl:1
	v_add_f32_dpp v177, v177, v177 quad_perm:[1,0,3,2] row_mask:0xf bank_mask:0xf bound_ctrl:1
	v_add_f32_dpp v178, v178, v178 quad_perm:[1,0,3,2] row_mask:0xf bank_mask:0xf bound_ctrl:1
	v_add_f32_dpp v175, v175, v175 quad_perm:[2,3,0,1] row_mask:0xf bank_mask:0xf bound_ctrl:1
	v_add_f32_dpp v176, v176, v176 quad_perm:[2,3,0,1] row_mask:0xf bank_mask:0xf bound_ctrl:1
	v_add_f32_dpp v177, v177, v177 quad_perm:[2,3,0,1] row_mask:0xf bank_mask:0xf bound_ctrl:1
	v_add_f32_dpp v178, v178, v178 quad_perm:[2,3,0,1] row_mask:0xf bank_mask:0xf bound_ctrl:1
	v_add_f32_dpp v175, v175, v175 row_half_mirror row_mask:0xf bank_mask:0xf bound_ctrl:1
	v_add_f32_dpp v176, v176, v176 row_half_mirror row_mask:0xf bank_mask:0xf bound_ctrl:1
	v_add_f32_dpp v177, v177, v177 row_half_mirror row_mask:0xf bank_mask:0xf bound_ctrl:1
	v_add_f32_dpp v178, v178, v178 row_half_mirror row_mask:0xf bank_mask:0xf bound_ctrl:1
	v_add_f32_dpp v175, v175, v175 row_mirror row_mask:0xf bank_mask:0xf bound_ctrl:1
	v_add_f32_dpp v176, v176, v176 row_mirror row_mask:0xf bank_mask:0xf bound_ctrl:1
	v_add_f32_dpp v177, v177, v177 row_mirror row_mask:0xf bank_mask:0xf bound_ctrl:1
	v_add_f32_dpp v178, v178, v178 row_mirror row_mask:0xf bank_mask:0xf bound_ctrl:1
	v_fmamk_f32 v175, v175, 0x3c000000, v163
	v_fmamk_f32 v176, v176, 0x3c000000, v163
	v_fmamk_f32 v177, v177, 0x3c000000, v163
	v_fmamk_f32 v178, v178, 0x3c000000, v163
	v_rsq_f32_e32 v175, v175
	v_rsq_f32_e32 v176, v176
	v_rsq_f32_e32 v177, v177
	v_rsq_f32_e32 v178, v178
	s_nop 0
	v_mul_f32_e32 v30, v30, v175
	v_mul_f32_e32 v31, v31, v176
	v_mul_f32_e32 v32, v32, v177
	v_mul_f32_e32 v33, v33, v178
	v_mul_f32_e32 v22, v22, v175
	v_mul_f32_e32 v23, v23, v176
	v_mul_f32_e32 v24, v24, v177
	v_mul_f32_e32 v25, v25, v178
	v_mul_f32_e32 v14, v14, v175
	v_mul_f32_e32 v15, v15, v176
	v_mul_f32_e32 v16, v16, v177
	v_mul_f32_e32 v17, v17, v178
	v_mul_f32_e32 v10, v10, v175
	v_mul_f32_e32 v11, v11, v176
	v_mul_f32_e32 v12, v12, v177
	v_mul_f32_e32 v13, v13, v178
	v_mul_f32_e32 v26, v26, v175
	v_mul_f32_e32 v27, v27, v176
	v_mul_f32_e32 v28, v28, v177
	v_mul_f32_e32 v29, v29, v178
	v_mul_f32_e32 v18, v18, v175
	v_mul_f32_e32 v19, v19, v176
	v_mul_f32_e32 v20, v20, v177
	v_mul_f32_e32 v21, v21, v178
	v_mul_f32_e32 v2, v2, v175
	v_mul_f32_e32 v3, v3, v176
	v_mul_f32_e32 v4, v4, v177
	v_mul_f32_e32 v5, v5, v178
	v_mul_f32_e32 v6, v6, v175
	v_mul_f32_e32 v7, v7, v176
	v_mul_f32_e32 v8, v8, v177
	v_mul_f32_e32 v9, v9, v178
	ds_write_b32 v167, v30
	ds_write_b32 v167, v22 offset:64
	ds_write_b32 v167, v14 offset:128
	ds_write_b32 v167, v10 offset:192
	ds_write_b32 v167, v31 offset:272
	ds_write_b32 v167, v23 offset:336
	ds_write_b32 v167, v15 offset:400
	ds_write_b32 v167, v11 offset:464
	ds_write_b32 v167, v32 offset:544
	ds_write_b32 v167, v24 offset:608
	ds_write_b32 v167, v16 offset:672
	ds_write_b32 v167, v12 offset:736
	ds_write_b32 v167, v33 offset:816
	ds_write_b32 v167, v25 offset:880
	ds_write_b32 v167, v17 offset:944
	ds_write_b32 v167, v13 offset:1008
	s_waitcnt lgkmcnt(0)
	ds_read_b128 v[184:187], v170
	ds_read_b128 v[188:191], v170 offset:16
	ds_read_b128 v[192:195], v170 offset:32
	ds_read_b128 v[196:199], v170 offset:48
	s_waitcnt vmcnt(2) lgkmcnt(0)
	v_lshlrev_b32_e32 v220, 16, v200
	v_and_b32_e32 v221, 0xffff0000, v200
	v_lshlrev_b32_e32 v222, 16, v201
	v_and_b32_e32 v223, 0xffff0000, v201
	v_mul_f32_e32 v232, 0xbfb8aa3b, v220
	v_mul_f32_e32 v233, 0xbfb8aa3b, v221
	v_mul_f32_e32 v234, 0xbfb8aa3b, v222
	v_mul_f32_e32 v235, 0xbfb8aa3b, v223
	v_exp_f32_e32 v232, v232
	v_exp_f32_e32 v233, v233
	v_exp_f32_e32 v234, v234
	v_exp_f32_e32 v235, v235
	s_nop 0
	v_add_f32_e32 v232, 1.0, v232
	v_add_f32_e32 v233, 1.0, v233
	v_add_f32_e32 v234, 1.0, v234
	v_add_f32_e32 v235, 1.0, v235
	v_rcp_f32_e32 v232, v232
	v_rcp_f32_e32 v233, v233
	v_rcp_f32_e32 v234, v234
	v_rcp_f32_e32 v235, v235
	s_nop 0
	v_mul_f32_e32 v220, v232, v220
	v_mul_f32_e32 v221, v233, v221
	v_mul_f32_e32 v222, v234, v222
	v_mul_f32_e32 v223, v235, v223
	v_mul_f32_e32 v220, v220, v184
	v_mul_f32_e32 v221, v221, v185
	v_mul_f32_e32 v222, v222, v186
	v_mul_f32_e32 v223, v223, v187
	v_cvt_pk_bf16_f32 v208, v220, v221
	v_cvt_pk_bf16_f32 v209, v222, v223
	v_lshlrev_b32_e32 v220, 16, v202
	v_and_b32_e32 v221, 0xffff0000, v202
	v_lshlrev_b32_e32 v222, 16, v203
	v_and_b32_e32 v223, 0xffff0000, v203
	v_mul_f32_e32 v232, 0xbfb8aa3b, v220
	v_mul_f32_e32 v233, 0xbfb8aa3b, v221
	v_mul_f32_e32 v234, 0xbfb8aa3b, v222
	v_mul_f32_e32 v235, 0xbfb8aa3b, v223
	v_exp_f32_e32 v232, v232
	v_exp_f32_e32 v233, v233
	v_exp_f32_e32 v234, v234
	v_exp_f32_e32 v235, v235
	s_nop 0
	v_add_f32_e32 v232, 1.0, v232
	v_add_f32_e32 v233, 1.0, v233
	v_add_f32_e32 v234, 1.0, v234
	v_add_f32_e32 v235, 1.0, v235
	v_rcp_f32_e32 v232, v232
	v_rcp_f32_e32 v233, v233
	v_rcp_f32_e32 v234, v234
	v_rcp_f32_e32 v235, v235
	s_nop 0
	v_mul_f32_e32 v220, v232, v220
	v_mul_f32_e32 v221, v233, v221
	v_mul_f32_e32 v222, v234, v222
	v_mul_f32_e32 v223, v235, v223
	v_mul_f32_e32 v220, v220, v188
	v_mul_f32_e32 v221, v221, v189
	v_mul_f32_e32 v222, v222, v190
	v_mul_f32_e32 v223, v223, v191
	v_cvt_pk_bf16_f32 v210, v220, v221
	v_cvt_pk_bf16_f32 v211, v222, v223
	v_lshlrev_b32_e32 v220, 16, v204
	v_and_b32_e32 v221, 0xffff0000, v204
	v_lshlrev_b32_e32 v222, 16, v205
	v_and_b32_e32 v223, 0xffff0000, v205
	v_mul_f32_e32 v232, 0xbfb8aa3b, v220
	v_mul_f32_e32 v233, 0xbfb8aa3b, v221
	v_mul_f32_e32 v234, 0xbfb8aa3b, v222
	v_mul_f32_e32 v235, 0xbfb8aa3b, v223
	v_exp_f32_e32 v232, v232
	v_exp_f32_e32 v233, v233
	v_exp_f32_e32 v234, v234
	v_exp_f32_e32 v235, v235
	s_nop 0
	v_add_f32_e32 v232, 1.0, v232
	v_add_f32_e32 v233, 1.0, v233
	v_add_f32_e32 v234, 1.0, v234
	v_add_f32_e32 v235, 1.0, v235
	v_rcp_f32_e32 v232, v232
	v_rcp_f32_e32 v233, v233
	v_rcp_f32_e32 v234, v234
	v_rcp_f32_e32 v235, v235
	s_nop 0
	v_mul_f32_e32 v220, v232, v220
	v_mul_f32_e32 v221, v233, v221
	v_mul_f32_e32 v222, v234, v222
	v_mul_f32_e32 v223, v235, v223
	v_mul_f32_e32 v220, v220, v192
	v_mul_f32_e32 v221, v221, v193
	v_mul_f32_e32 v222, v222, v194
	v_mul_f32_e32 v223, v223, v195
	v_cvt_pk_bf16_f32 v216, v220, v221
	v_cvt_pk_bf16_f32 v217, v222, v223
	v_lshlrev_b32_e32 v220, 16, v206
	v_and_b32_e32 v221, 0xffff0000, v206
	v_lshlrev_b32_e32 v222, 16, v207
	v_and_b32_e32 v223, 0xffff0000, v207
	v_mul_f32_e32 v232, 0xbfb8aa3b, v220
	v_mul_f32_e32 v233, 0xbfb8aa3b, v221
	v_mul_f32_e32 v234, 0xbfb8aa3b, v222
	v_mul_f32_e32 v235, 0xbfb8aa3b, v223
	v_exp_f32_e32 v232, v232
	v_exp_f32_e32 v233, v233
	v_exp_f32_e32 v234, v234
	v_exp_f32_e32 v235, v235
	s_nop 0
	v_add_f32_e32 v232, 1.0, v232
	v_add_f32_e32 v233, 1.0, v233
	v_add_f32_e32 v234, 1.0, v234
	v_add_f32_e32 v235, 1.0, v235
	v_rcp_f32_e32 v232, v232
	v_rcp_f32_e32 v233, v233
	v_rcp_f32_e32 v234, v234
	v_rcp_f32_e32 v235, v235
	s_nop 0
	v_mul_f32_e32 v220, v232, v220
	v_mul_f32_e32 v221, v233, v221
	v_mul_f32_e32 v222, v234, v222
	v_mul_f32_e32 v223, v235, v223
	v_mul_f32_e32 v220, v220, v196
	v_mul_f32_e32 v221, v221, v197
	v_mul_f32_e32 v222, v222, v198
	v_mul_f32_e32 v223, v223, v199
	v_cvt_pk_bf16_f32 v218, v220, v221
	v_cvt_pk_bf16_f32 v219, v222, v223
	global_store_dwordx4 v173, v[208:211], s[4:5]
	global_store_dwordx4 v173, v[216:219], s[4:5] offset:16
	ds_write_b32 v167, v26
	ds_write_b32 v167, v18 offset:64
	ds_write_b32 v167, v2 offset:128
	ds_write_b32 v167, v6 offset:192
	ds_write_b32 v167, v27 offset:272
	ds_write_b32 v167, v19 offset:336
	ds_write_b32 v167, v3 offset:400
	ds_write_b32 v167, v7 offset:464
	ds_write_b32 v167, v28 offset:544
	ds_write_b32 v167, v20 offset:608
	ds_write_b32 v167, v4 offset:672
	ds_write_b32 v167, v8 offset:736
	ds_write_b32 v167, v29 offset:816
	ds_write_b32 v167, v21 offset:880
	ds_write_b32 v167, v5 offset:944
	ds_write_b32 v167, v9 offset:1008
	s_waitcnt lgkmcnt(0)
	ds_read_b128 v[184:187], v170
	ds_read_b128 v[188:191], v170 offset:16
	ds_read_b128 v[192:195], v170 offset:32
	ds_read_b128 v[196:199], v170 offset:48
	s_waitcnt vmcnt(2) lgkmcnt(0)
	v_lshlrev_b32_e32 v220, 16, v224
	v_and_b32_e32 v221, 0xffff0000, v224
	v_lshlrev_b32_e32 v222, 16, v225
	v_and_b32_e32 v223, 0xffff0000, v225
	v_mul_f32_e32 v232, 0xbfb8aa3b, v220
	v_mul_f32_e32 v233, 0xbfb8aa3b, v221
	v_mul_f32_e32 v234, 0xbfb8aa3b, v222
	v_mul_f32_e32 v235, 0xbfb8aa3b, v223
	v_exp_f32_e32 v232, v232
	v_exp_f32_e32 v233, v233
	v_exp_f32_e32 v234, v234
	v_exp_f32_e32 v235, v235
	s_nop 0
	v_add_f32_e32 v232, 1.0, v232
	v_add_f32_e32 v233, 1.0, v233
	v_add_f32_e32 v234, 1.0, v234
	v_add_f32_e32 v235, 1.0, v235
	v_rcp_f32_e32 v232, v232
	v_rcp_f32_e32 v233, v233
	v_rcp_f32_e32 v234, v234
	v_rcp_f32_e32 v235, v235
	s_nop 0
	v_mul_f32_e32 v220, v232, v220
	v_mul_f32_e32 v221, v233, v221
	v_mul_f32_e32 v222, v234, v222
	v_mul_f32_e32 v223, v235, v223
	v_mul_f32_e32 v220, v220, v184
	v_mul_f32_e32 v221, v221, v185
	v_mul_f32_e32 v222, v222, v186
	v_mul_f32_e32 v223, v223, v187
	v_cvt_pk_bf16_f32 v208, v220, v221
	v_cvt_pk_bf16_f32 v209, v222, v223
	v_lshlrev_b32_e32 v220, 16, v226
	v_and_b32_e32 v221, 0xffff0000, v226
	v_lshlrev_b32_e32 v222, 16, v227
	v_and_b32_e32 v223, 0xffff0000, v227
	v_mul_f32_e32 v232, 0xbfb8aa3b, v220
	v_mul_f32_e32 v233, 0xbfb8aa3b, v221
	v_mul_f32_e32 v234, 0xbfb8aa3b, v222
	v_mul_f32_e32 v235, 0xbfb8aa3b, v223
	v_exp_f32_e32 v232, v232
	v_exp_f32_e32 v233, v233
	v_exp_f32_e32 v234, v234
	v_exp_f32_e32 v235, v235
	s_nop 0
	v_add_f32_e32 v232, 1.0, v232
	v_add_f32_e32 v233, 1.0, v233
	v_add_f32_e32 v234, 1.0, v234
	v_add_f32_e32 v235, 1.0, v235
	v_rcp_f32_e32 v232, v232
	v_rcp_f32_e32 v233, v233
	v_rcp_f32_e32 v234, v234
	v_rcp_f32_e32 v235, v235
	s_nop 0
	v_mul_f32_e32 v220, v232, v220
	v_mul_f32_e32 v221, v233, v221
	v_mul_f32_e32 v222, v234, v222
	v_mul_f32_e32 v223, v235, v223
	v_mul_f32_e32 v220, v220, v188
	v_mul_f32_e32 v221, v221, v189
	v_mul_f32_e32 v222, v222, v190
	v_mul_f32_e32 v223, v223, v191
	v_cvt_pk_bf16_f32 v210, v220, v221
	v_cvt_pk_bf16_f32 v211, v222, v223
	v_lshlrev_b32_e32 v220, 16, v228
	v_and_b32_e32 v221, 0xffff0000, v228
	v_lshlrev_b32_e32 v222, 16, v229
	v_and_b32_e32 v223, 0xffff0000, v229
	v_mul_f32_e32 v232, 0xbfb8aa3b, v220
	v_mul_f32_e32 v233, 0xbfb8aa3b, v221
	v_mul_f32_e32 v234, 0xbfb8aa3b, v222
	v_mul_f32_e32 v235, 0xbfb8aa3b, v223
	v_exp_f32_e32 v232, v232
	v_exp_f32_e32 v233, v233
	v_exp_f32_e32 v234, v234
	v_exp_f32_e32 v235, v235
	s_nop 0
	v_add_f32_e32 v232, 1.0, v232
	v_add_f32_e32 v233, 1.0, v233
	v_add_f32_e32 v234, 1.0, v234
	v_add_f32_e32 v235, 1.0, v235
	v_rcp_f32_e32 v232, v232
	v_rcp_f32_e32 v233, v233
	v_rcp_f32_e32 v234, v234
	v_rcp_f32_e32 v235, v235
	s_nop 0
	v_mul_f32_e32 v220, v232, v220
	v_mul_f32_e32 v221, v233, v221
	v_mul_f32_e32 v222, v234, v222
	v_mul_f32_e32 v223, v235, v223
	v_mul_f32_e32 v220, v220, v192
	v_mul_f32_e32 v221, v221, v193
	v_mul_f32_e32 v222, v222, v194
	v_mul_f32_e32 v223, v223, v195
	v_cvt_pk_bf16_f32 v216, v220, v221
	v_cvt_pk_bf16_f32 v217, v222, v223
	v_lshlrev_b32_e32 v220, 16, v230
	v_and_b32_e32 v221, 0xffff0000, v230
	v_lshlrev_b32_e32 v222, 16, v231
	v_and_b32_e32 v223, 0xffff0000, v231
	v_mul_f32_e32 v232, 0xbfb8aa3b, v220
	v_mul_f32_e32 v233, 0xbfb8aa3b, v221
	v_mul_f32_e32 v234, 0xbfb8aa3b, v222
	v_mul_f32_e32 v235, 0xbfb8aa3b, v223
	v_exp_f32_e32 v232, v232
	v_exp_f32_e32 v233, v233
	v_exp_f32_e32 v234, v234
	v_exp_f32_e32 v235, v235
	s_nop 0
	v_add_f32_e32 v232, 1.0, v232
	v_add_f32_e32 v233, 1.0, v233
	v_add_f32_e32 v234, 1.0, v234
	v_add_f32_e32 v235, 1.0, v235
	v_rcp_f32_e32 v232, v232
	v_rcp_f32_e32 v233, v233
	v_rcp_f32_e32 v234, v234
	v_rcp_f32_e32 v235, v235
	s_nop 0
	v_mul_f32_e32 v220, v232, v220
	v_mul_f32_e32 v221, v233, v221
	v_mul_f32_e32 v222, v234, v222
	v_mul_f32_e32 v223, v235, v223
	v_mul_f32_e32 v220, v220, v196
	v_mul_f32_e32 v221, v221, v197
	v_mul_f32_e32 v222, v222, v198
	v_mul_f32_e32 v223, v223, v199
	v_cvt_pk_bf16_f32 v218, v220, v221
	v_cvt_pk_bf16_f32 v219, v222, v223
	global_store_dwordx4 v173, v[208:211], s[4:5] offset:128
	global_store_dwordx4 v173, v[216:219], s[4:5] offset:144
